# v69 stack with every s_setprio removed from the GEMM main loop (A/B of hipcc's per-phase priority flips on the stacked kernel)
# speedup vs baseline: 1.0017x; 1.0017x over previous
; #define PG8_STAGE(bufoff, gbase, voff) do { _Pragma("unroll") for (int _i = 0; _i < 2; ++_i) \
;         __builtin_amdgcn_global_load_lds((const unsigned*)((const char*)(gbase) + (voff)[_i]), (LAS unsigned*)(lds + (bufoff) + ldsw + _i * 8192), 16, 0, 0); } while (0)
; #define PG8_LDA(dst, b, h) do { _Pragma("unroll") for (int m = 0; m < 4; ++m) _Pragma("unroll") for (int k = 0; k < 2; ++k) dst[m][k] = *(const LAS bf16x8*)(lds + PG8_SA(b, h) + aoff + m * 2048 + k * 1024); } while (0)
; #define PG8_LDB(dst, b, h) do { _Pragma("unroll") for (int n = 0; n < 2; ++n) _Pragma("unroll") for (int k = 0; k < 2; ++k) dst[n][k] = *(const LAS bf16x8*)(lds + PG8_SB(b, h) + boff + n * 2048 + k * 1024); } while (0)
; #define PG8_MMA(ai, bj, At, Bt) do { __builtin_amdgcn_s_setprio(1); _Pragma("unroll") for (int m = 0; m < 4; ++m) _Pragma("unroll") for (int n = 0; n < 2; ++n) _Pragma("unroll") for (int k = 0; k < 2; ++k) \
;         acc[ai][bj][m][n] = __builtin_amdgcn_mfma_f32_16x16x32_bf16(Bt[n][k], At[m][k], acc[ai][bj][m][n], 0, 0, 0); __builtin_amdgcn_s_setprio(0); } while (0)
; #define PG8_WAIT_V(n) asm volatile("s_waitcnt vmcnt(" #n ")" ::: "memory")
; #define PG8_WAIT_L(n) asm volatile("s_waitcnt lgkmcnt(" #n ")" ::: "memory")
; #define PG8_BAR __builtin_amdgcn_s_barrier()
; #define PG8_SCHED __builtin_amdgcn_sched_barrier(0)
; __device__ __forceinline__ void gemm_phase(LAS unsigned char* lds, const Gemm g, const StaticOrder& S, const Epi& E) {
;     ...
;             PG8_LDB(B0, 0, 0); PG8_LDB(B1, 0, 1); PG8_SCHED; PG8_LDA(At, 0, 0); PG8_STAGE(PG8_SA(1, 1), a1 + hstepA, voffA);
;             PG8_WAIT_V(8); PG8_WAIT_L(0); PG8_BAR; PG8_MMA(0, 0, At, B0); PG8_MMA(0, 1, At, B1); PG8_BAR; PG8_SCHED;
;             PG8_LDA(At, 0, 1); PG8_STAGE(PG8_SB(0, 0), b2, voffB); PG8_STAGE(PG8_SB(0, 1), b2 + hstepB, voffB); PG8_STAGE(PG8_SA(0, 0), a2, voffA);
;             PG8_WAIT_V(8); PG8_WAIT_L(0); PG8_BAR; PG8_MMA(1, 0, At, B0); PG8_MMA(1, 1, At, B1); PG8_BAR; PG8_SCHED;
.LBB0_177:
	s_waitcnt lgkmcnt(0)
	ds_read_b128 v[130:133], v226
	ds_read_b128 v[134:137], v226 offset:1024
	ds_read_b128 v[138:141], v226 offset:2048
	ds_read_b128 v[142:145], v226 offset:3072
	ds_read_b128 v[146:149], v227
	ds_read_b128 v[150:153], v227 offset:1024
	ds_read_b128 v[154:157], v227 offset:2048
	ds_read_b128 v[182:185], v227 offset:3072
	s_add_i32 s27, s17, 2
	s_add_u32 s2, s0, 0x80
	s_addc_u32 s3, s1, 0
	s_cmp_eq_u32 s85, s17
	s_cselect_b32 s3, s7, s3
	s_cselect_b32 s2, s6, s2
	s_cselect_b32 s41, s95, s16
	s_cselect_b32 s40, s94, s5
	s_add_i32 m0, s71, 0xc000
	ds_read_b128 v[186:189], v217
	ds_read_b128 v[190:193], v217 offset:1024
	ds_read_b128 v[194:197], v217 offset:2048
	ds_read_b128 v[198:201], v217 offset:3072
	ds_read_b128 v[202:205], v217 offset:4096
	ds_read_b128 v[206:209], v217 offset:5120
	ds_read_b128 v[218:221], v217 offset:6144
	ds_read_b128 v[222:225], v217 offset:7168
	global_load_lds_dwordx4 v178, s[0:1]
	s_add_i32 m0, s71, 0xe000
	s_nop 0
	global_load_lds_dwordx4 v180, s[0:1]
	s_waitcnt vmcnt(8)
	s_waitcnt lgkmcnt(0)
	s_barrier
	v_mfma_f32_16x16x32_bf16 v[114:117], v[130:133], v[186:189], v[114:117]
	v_mfma_f32_16x16x32_bf16 v[126:129], v[138:141], v[186:189], v[126:129]
	v_mfma_f32_16x16x32_bf16 v[110:113], v[130:133], v[194:197], v[110:113]
	v_mfma_f32_16x16x32_bf16 v[102:105], v[138:141], v[194:197], v[102:105]
	v_mfma_f32_16x16x32_bf16 v[94:97], v[130:133], v[202:205], v[94:97]
	v_mfma_f32_16x16x32_bf16 v[86:89], v[138:141], v[202:205], v[86:89]
	v_mfma_f32_16x16x32_bf16 v[78:81], v[130:133], v[218:221], v[78:81]
	v_mfma_f32_16x16x32_bf16 v[70:73], v[138:141], v[218:221], v[70:73]
	v_mfma_f32_16x16x32_bf16 v[114:117], v[134:137], v[190:193], v[114:117]
	v_mfma_f32_16x16x32_bf16 v[126:129], v[142:145], v[190:193], v[126:129]
	v_mfma_f32_16x16x32_bf16 v[110:113], v[134:137], v[198:201], v[110:113]
	v_mfma_f32_16x16x32_bf16 v[102:105], v[142:145], v[198:201], v[102:105]
	v_mfma_f32_16x16x32_bf16 v[94:97], v[134:137], v[206:209], v[94:97]
	v_mfma_f32_16x16x32_bf16 v[86:89], v[142:145], v[206:209], v[86:89]
	v_mfma_f32_16x16x32_bf16 v[78:81], v[134:137], v[222:225], v[78:81]
	v_mfma_f32_16x16x32_bf16 v[70:73], v[142:145], v[222:225], v[70:73]
	v_mfma_f32_16x16x32_bf16 v[122:125], v[146:149], v[186:189], v[122:125]
	v_mfma_f32_16x16x32_bf16 v[118:121], v[154:157], v[186:189], v[118:121]
	v_mfma_f32_16x16x32_bf16 v[106:109], v[146:149], v[194:197], v[106:109]
	v_mfma_f32_16x16x32_bf16 v[98:101], v[154:157], v[194:197], v[98:101]
	v_mfma_f32_16x16x32_bf16 v[90:93], v[146:149], v[202:205], v[90:93]
	v_mfma_f32_16x16x32_bf16 v[82:85], v[154:157], v[202:205], v[82:85]
	v_mfma_f32_16x16x32_bf16 v[74:77], v[146:149], v[218:221], v[74:77]
	v_mfma_f32_16x16x32_bf16 v[66:69], v[154:157], v[218:221], v[66:69]
	v_mfma_f32_16x16x32_bf16 v[122:125], v[150:153], v[190:193], v[122:125]
	v_mfma_f32_16x16x32_bf16 v[118:121], v[182:185], v[190:193], v[118:121]
	v_mfma_f32_16x16x32_bf16 v[106:109], v[150:153], v[198:201], v[106:109]
	v_mfma_f32_16x16x32_bf16 v[98:101], v[182:185], v[198:201], v[98:101]
	v_mfma_f32_16x16x32_bf16 v[90:93], v[150:153], v[206:209], v[90:93]
	v_mfma_f32_16x16x32_bf16 v[82:85], v[182:185], v[206:209], v[82:85]
	v_mfma_f32_16x16x32_bf16 v[74:77], v[150:153], v[222:225], v[74:77]
	v_mfma_f32_16x16x32_bf16 v[66:69], v[182:185], v[222:225], v[66:69]
	s_barrier
	s_add_i32 s17, s39, s70
	s_mov_b32 m0, s17
	ds_read_b128 v[186:189], v217 offset:16384
	ds_read_b128 v[190:193], v217 offset:17408
	ds_read_b128 v[194:197], v217 offset:18432
	ds_read_b128 v[198:201], v217 offset:19456
	ds_read_b128 v[202:205], v217 offset:20480
	ds_read_b128 v[206:209], v217 offset:21504
	ds_read_b128 v[218:221], v217 offset:22528
	ds_read_b128 v[222:225], v217 offset:23552
	global_load_lds_dwordx4 v160, s[40:41]
	s_add_i32 m0, s17, 0x2000
	s_add_i32 s17, s24, s70
	global_load_lds_dwordx4 v164, s[40:41]
	s_add_u32 s40, s40, s52
	s_addc_u32 s41, s41, s53
	s_mov_b32 m0, s17
	s_nop 0
	global_load_lds_dwordx4 v160, s[40:41]
	s_add_i32 m0, s17, 0x2000
	s_nop 0
	global_load_lds_dwordx4 v164, s[40:41]
	s_mov_b32 m0, s71
	s_nop 0
	global_load_lds_dwordx4 v158, s[2:3]
	s_mov_b32 m0, s34
	s_nop 0
	global_load_lds_dwordx4 v162, s[2:3]
	s_waitcnt vmcnt(8)
	s_waitcnt lgkmcnt(0)
	s_barrier
	v_mfma_f32_16x16x32_bf16 v[62:65], v[130:133], v[186:189], v[62:65]
	v_mfma_f32_16x16x32_bf16 v[54:57], v[138:141], v[186:189], v[54:57]
	v_mfma_f32_16x16x32_bf16 v[46:49], v[130:133], v[194:197], v[46:49]
	v_mfma_f32_16x16x32_bf16 v[38:41], v[138:141], v[194:197], v[38:41]
	v_mfma_f32_16x16x32_bf16 v[30:33], v[130:133], v[202:205], v[30:33]
	v_mfma_f32_16x16x32_bf16 v[22:25], v[138:141], v[202:205], v[22:25]
	v_mfma_f32_16x16x32_bf16 v[14:17], v[130:133], v[218:221], v[14:17]
	v_mfma_f32_16x16x32_bf16 v[6:9], v[138:141], v[218:221], v[6:9]
	v_mfma_f32_16x16x32_bf16 v[62:65], v[134:137], v[190:193], v[62:65]
	v_mfma_f32_16x16x32_bf16 v[54:57], v[142:145], v[190:193], v[54:57]
	v_mfma_f32_16x16x32_bf16 v[46:49], v[134:137], v[198:201], v[46:49]
	v_mfma_f32_16x16x32_bf16 v[38:41], v[142:145], v[198:201], v[38:41]
	v_mfma_f32_16x16x32_bf16 v[30:33], v[134:137], v[206:209], v[30:33]
	v_mfma_f32_16x16x32_bf16 v[22:25], v[142:145], v[206:209], v[22:25]
	v_mfma_f32_16x16x32_bf16 v[14:17], v[134:137], v[222:225], v[14:17]
	v_mfma_f32_16x16x32_bf16 v[6:9], v[142:145], v[222:225], v[6:9]
	v_mfma_f32_16x16x32_bf16 v[58:61], v[146:149], v[186:189], v[58:61]
	v_mfma_f32_16x16x32_bf16 v[50:53], v[154:157], v[186:189], v[50:53]
	v_mfma_f32_16x16x32_bf16 v[42:45], v[146:149], v[194:197], v[42:45]
	v_mfma_f32_16x16x32_bf16 v[34:37], v[154:157], v[194:197], v[34:37]
	v_mfma_f32_16x16x32_bf16 v[26:29], v[146:149], v[202:205], v[26:29]
	v_mfma_f32_16x16x32_bf16 v[18:21], v[154:157], v[202:205], v[18:21]
	v_mfma_f32_16x16x32_bf16 v[10:13], v[146:149], v[218:221], v[10:13]
	v_mfma_f32_16x16x32_bf16 v[2:5], v[154:157], v[218:221], v[2:5]
	v_mfma_f32_16x16x32_bf16 v[58:61], v[150:153], v[190:193], v[58:61]
	v_mfma_f32_16x16x32_bf16 v[50:53], v[182:185], v[190:193], v[50:53]
	v_mfma_f32_16x16x32_bf16 v[42:45], v[150:153], v[198:201], v[42:45]
	v_mfma_f32_16x16x32_bf16 v[34:37], v[182:185], v[198:201], v[34:37]
	v_mfma_f32_16x16x32_bf16 v[26:29], v[150:153], v[206:209], v[26:29]
	v_mfma_f32_16x16x32_bf16 v[18:21], v[182:185], v[206:209], v[18:21]
	v_mfma_f32_16x16x32_bf16 v[10:13], v[150:153], v[222:225], v[10:13]
	v_mfma_f32_16x16x32_bf16 v[2:5], v[182:185], v[222:225], v[2:5]
	s_barrier
; #define PG8_STAGE(bufoff, gbase, voff) do { _Pragma("unroll") for (int _i = 0; _i < 2; ++_i) \
;         __builtin_amdgcn_global_load_lds((const unsigned*)((const char*)(gbase) + (voff)[_i]), (LAS unsigned*)(lds + (bufoff) + ldsw + _i * 8192), 16, 0, 0); } while (0)
; #define PG8_LDA(dst, b, h) do { _Pragma("unroll") for (int m = 0; m < 4; ++m) _Pragma("unroll") for (int k = 0; k < 2; ++k) dst[m][k] = *(const LAS bf16x8*)(lds + PG8_SA(b, h) + aoff + m * 2048 + k * 1024); } while (0)
; #define PG8_LDB(dst, b, h) do { _Pragma("unroll") for (int n = 0; n < 2; ++n) _Pragma("unroll") for (int k = 0; k < 2; ++k) dst[n][k] = *(const LAS bf16x8*)(lds + PG8_SB(b, h) + boff + n * 2048 + k * 1024); } while (0)
; #define PG8_MMA(ai, bj, At, Bt) do { __builtin_amdgcn_s_setprio(1); _Pragma("unroll") for (int m = 0; m < 4; ++m) _Pragma("unroll") for (int n = 0; n < 2; ++n) _Pragma("unroll") for (int k = 0; k < 2; ++k) \
;         acc[ai][bj][m][n] = __builtin_amdgcn_mfma_f32_16x16x32_bf16(Bt[n][k], At[m][k], acc[ai][bj][m][n], 0, 0, 0); __builtin_amdgcn_s_setprio(0); } while (0)
; #define PG8_WAIT_V(n) asm volatile("s_waitcnt vmcnt(" #n ")" ::: "memory")
; #define PG8_WAIT_L(n) asm volatile("s_waitcnt lgkmcnt(" #n ")" ::: "memory")
; #define PG8_BAR __builtin_amdgcn_s_barrier()
; #define PG8_SCHED __builtin_amdgcn_sched_barrier(0)
; __device__ __forceinline__ void gemm_phase(LAS unsigned char* lds, const Gemm g, const StaticOrder& S, const Epi& E) {
;     ...
;             PG8_LDB(B0, 1, 0); PG8_LDB(B1, 1, 1); PG8_SCHED; PG8_LDA(At, 1, 0); PG8_STAGE(PG8_SA(0, 1), a2 + hstepA, voffA);
;             PG8_WAIT_V(8); PG8_WAIT_L(0); PG8_BAR; PG8_MMA(0, 0, At, B0); PG8_MMA(0, 1, At, B1); PG8_BAR; PG8_SCHED;
;             PG8_LDA(At, 1, 1); PG8_STAGE(PG8_SB(1, 0), b3, voffB); PG8_STAGE(PG8_SB(1, 1), b3 + hstepB, voffB); PG8_STAGE(PG8_SA(1, 0), a3, voffA);
;             PG8_WAIT_V(8); PG8_WAIT_L(0); PG8_BAR; PG8_MMA(1, 0, At, B0); PG8_MMA(1, 1, At, B1); PG8_BAR; PG8_SCHED;
	ds_read_b128 v[130:133], v228
	ds_read_b128 v[134:137], v228 offset:1024
	ds_read_b128 v[138:141], v228 offset:2048
	ds_read_b128 v[142:145], v228 offset:3072
	ds_read_b128 v[146:149], v229
	ds_read_b128 v[150:153], v229 offset:1024
	ds_read_b128 v[154:157], v229 offset:2048
	ds_read_b128 v[182:185], v229 offset:3072
	s_mov_b32 m0, s92
	ds_read_b128 v[186:189], v217 offset:32768
	ds_read_b128 v[190:193], v217 offset:33792
	ds_read_b128 v[194:197], v217 offset:34816
	ds_read_b128 v[198:201], v217 offset:35840
	ds_read_b128 v[202:205], v217 offset:36864
	ds_read_b128 v[206:209], v217 offset:37888
	ds_read_b128 v[218:221], v217 offset:38912
	ds_read_b128 v[222:225], v217 offset:39936
	global_load_lds_dwordx4 v178, s[2:3]
	s_mov_b32 m0, s93
	s_nop 0
	global_load_lds_dwordx4 v180, s[2:3]
	s_waitcnt vmcnt(8)
	s_waitcnt lgkmcnt(0)
	s_barrier
	v_mfma_f32_16x16x32_bf16 v[114:117], v[130:133], v[186:189], v[114:117]
	v_mfma_f32_16x16x32_bf16 v[126:129], v[138:141], v[186:189], v[126:129]
	v_mfma_f32_16x16x32_bf16 v[110:113], v[130:133], v[194:197], v[110:113]
	v_mfma_f32_16x16x32_bf16 v[102:105], v[138:141], v[194:197], v[102:105]
	v_mfma_f32_16x16x32_bf16 v[94:97], v[130:133], v[202:205], v[94:97]
	v_mfma_f32_16x16x32_bf16 v[86:89], v[138:141], v[202:205], v[86:89]
	v_mfma_f32_16x16x32_bf16 v[78:81], v[130:133], v[218:221], v[78:81]
	v_mfma_f32_16x16x32_bf16 v[70:73], v[138:141], v[218:221], v[70:73]
	v_mfma_f32_16x16x32_bf16 v[114:117], v[134:137], v[190:193], v[114:117]
	v_mfma_f32_16x16x32_bf16 v[126:129], v[142:145], v[190:193], v[126:129]
	v_mfma_f32_16x16x32_bf16 v[110:113], v[134:137], v[198:201], v[110:113]
	v_mfma_f32_16x16x32_bf16 v[102:105], v[142:145], v[198:201], v[102:105]
	v_mfma_f32_16x16x32_bf16 v[94:97], v[134:137], v[206:209], v[94:97]
	v_mfma_f32_16x16x32_bf16 v[86:89], v[142:145], v[206:209], v[86:89]
	v_mfma_f32_16x16x32_bf16 v[78:81], v[134:137], v[222:225], v[78:81]
	v_mfma_f32_16x16x32_bf16 v[70:73], v[142:145], v[222:225], v[70:73]
	v_mfma_f32_16x16x32_bf16 v[122:125], v[146:149], v[186:189], v[122:125]
	v_mfma_f32_16x16x32_bf16 v[118:121], v[154:157], v[186:189], v[118:121]
	v_mfma_f32_16x16x32_bf16 v[106:109], v[146:149], v[194:197], v[106:109]
	v_mfma_f32_16x16x32_bf16 v[98:101], v[154:157], v[194:197], v[98:101]
	v_mfma_f32_16x16x32_bf16 v[90:93], v[146:149], v[202:205], v[90:93]
	v_mfma_f32_16x16x32_bf16 v[82:85], v[154:157], v[202:205], v[82:85]
	v_mfma_f32_16x16x32_bf16 v[74:77], v[146:149], v[218:221], v[74:77]
	v_mfma_f32_16x16x32_bf16 v[66:69], v[154:157], v[218:221], v[66:69]
	v_mfma_f32_16x16x32_bf16 v[122:125], v[150:153], v[190:193], v[122:125]
	v_mfma_f32_16x16x32_bf16 v[118:121], v[182:185], v[190:193], v[118:121]
	v_mfma_f32_16x16x32_bf16 v[106:109], v[150:153], v[198:201], v[106:109]
	v_mfma_f32_16x16x32_bf16 v[98:101], v[182:185], v[198:201], v[98:101]
	v_mfma_f32_16x16x32_bf16 v[90:93], v[150:153], v[206:209], v[90:93]
	v_mfma_f32_16x16x32_bf16 v[82:85], v[182:185], v[206:209], v[82:85]
	v_mfma_f32_16x16x32_bf16 v[74:77], v[150:153], v[222:225], v[74:77]
	v_mfma_f32_16x16x32_bf16 v[66:69], v[182:185], v[222:225], v[66:69]
	s_barrier
	s_add_u32 s40, s40, 0x80
	s_addc_u32 s41, s41, 0
	s_sub_u32 s100, s40, s52
	s_subb_u32 s101, s41, s53
	s_add_u32 s2, s2, 0x80
	s_addc_u32 s3, s3, 0
	s_add_i32 vcc_lo, s25, s70
	s_mov_b32 m0, vcc_lo
	ds_read_b128 v[186:189], v217 offset:49152
	ds_read_b128 v[190:193], v217 offset:50176
	ds_read_b128 v[194:197], v217 offset:51200
	ds_read_b128 v[198:201], v217 offset:52224
	ds_read_b128 v[202:205], v217 offset:53248
	ds_read_b128 v[206:209], v217 offset:54272
	ds_read_b128 v[218:221], v217 offset:55296
	ds_read_b128 v[222:225], v217 offset:56320
	global_load_lds_dwordx4 v160, s[100:101]
	s_add_i32 m0, vcc_lo, 0x2000
	s_add_i32 vcc_lo, s26, s70
	global_load_lds_dwordx4 v164, s[100:101]
	s_mov_b32 m0, vcc_lo
	s_nop 0
	global_load_lds_dwordx4 v160, s[40:41]
	s_add_i32 m0, vcc_lo, 0x2000
	s_nop 0
	global_load_lds_dwordx4 v164, s[40:41]
	s_mov_b32 m0, s58
	s_nop 0
	global_load_lds_dwordx4 v158, s[2:3]
	s_mov_b32 m0, s59
	s_nop 0
	global_load_lds_dwordx4 v162, s[2:3]
	s_waitcnt vmcnt(8)
	s_waitcnt lgkmcnt(0)
	s_barrier
	v_mfma_f32_16x16x32_bf16 v[62:65], v[130:133], v[186:189], v[62:65]
	v_mfma_f32_16x16x32_bf16 v[54:57], v[138:141], v[186:189], v[54:57]
	v_mfma_f32_16x16x32_bf16 v[46:49], v[130:133], v[194:197], v[46:49]
	v_mfma_f32_16x16x32_bf16 v[38:41], v[138:141], v[194:197], v[38:41]
	v_mfma_f32_16x16x32_bf16 v[30:33], v[130:133], v[202:205], v[30:33]
	v_mfma_f32_16x16x32_bf16 v[22:25], v[138:141], v[202:205], v[22:25]
	v_mfma_f32_16x16x32_bf16 v[14:17], v[130:133], v[218:221], v[14:17]
	v_mfma_f32_16x16x32_bf16 v[6:9], v[138:141], v[218:221], v[6:9]
	v_mfma_f32_16x16x32_bf16 v[62:65], v[134:137], v[190:193], v[62:65]
	v_mfma_f32_16x16x32_bf16 v[54:57], v[142:145], v[190:193], v[54:57]
	v_mfma_f32_16x16x32_bf16 v[46:49], v[134:137], v[198:201], v[46:49]
	v_mfma_f32_16x16x32_bf16 v[38:41], v[142:145], v[198:201], v[38:41]
	v_mfma_f32_16x16x32_bf16 v[30:33], v[134:137], v[206:209], v[30:33]
	v_mfma_f32_16x16x32_bf16 v[22:25], v[142:145], v[206:209], v[22:25]
	v_mfma_f32_16x16x32_bf16 v[14:17], v[134:137], v[222:225], v[14:17]
	v_mfma_f32_16x16x32_bf16 v[6:9], v[142:145], v[222:225], v[6:9]
	v_mfma_f32_16x16x32_bf16 v[58:61], v[146:149], v[186:189], v[58:61]
	v_mfma_f32_16x16x32_bf16 v[50:53], v[154:157], v[186:189], v[50:53]
	v_mfma_f32_16x16x32_bf16 v[42:45], v[146:149], v[194:197], v[42:45]
	v_mfma_f32_16x16x32_bf16 v[34:37], v[154:157], v[194:197], v[34:37]
	v_mfma_f32_16x16x32_bf16 v[26:29], v[146:149], v[202:205], v[26:29]
	v_mfma_f32_16x16x32_bf16 v[18:21], v[154:157], v[202:205], v[18:21]
	v_mfma_f32_16x16x32_bf16 v[10:13], v[146:149], v[218:221], v[10:13]
	v_mfma_f32_16x16x32_bf16 v[2:5], v[154:157], v[218:221], v[2:5]
	v_mfma_f32_16x16x32_bf16 v[58:61], v[150:153], v[190:193], v[58:61]
	v_mfma_f32_16x16x32_bf16 v[50:53], v[182:185], v[190:193], v[50:53]
	v_mfma_f32_16x16x32_bf16 v[42:45], v[150:153], v[198:201], v[42:45]
	v_mfma_f32_16x16x32_bf16 v[34:37], v[182:185], v[198:201], v[34:37]
	v_mfma_f32_16x16x32_bf16 v[26:29], v[150:153], v[206:209], v[26:29]
	v_mfma_f32_16x16x32_bf16 v[18:21], v[182:185], v[206:209], v[18:21]
	v_mfma_f32_16x16x32_bf16 v[10:13], v[150:153], v[222:225], v[10:13]
	v_mfma_f32_16x16x32_bf16 v[2:5], v[182:185], v[222:225], v[2:5]
	s_barrier
	s_add_u32 s0, s0, 0x100
	s_addc_u32 s1, s1, 0
	s_add_u32 s5, s5, 0x100
	s_addc_u32 s16, s16, 0
	s_cmp_ge_i32 s27, s84
	s_mov_b32 s17, s27
	s_cbranch_scc0 .LBB0_177
	s_and_b64 vcc, exec, s[74:75]
	s_cbranch_vccz .LBB0_180
